# v013_prepcv
# baseline (speedup 1.0000x reference)
; __device__ __forceinline__ void rmsnorm_rows(const float* __restrict__ xin, const float* __restrict__ g, u16* outb, float* outf,
;                                              int row_begin, int row_end, int row_step, const int tidx) {
;   const int lane = tidx & 63;
;   f32x4 ggv[16];
; #pragma unroll
;   for (int i = 0; i < 16; ++i) ggv[i] = *reinterpret_cast<const f32x4*>(g + i * 256 + lane * 4);
; #pragma unroll 1
;   for (int row = row_begin; row < row_end; row += row_step) {
;     const float* xr = xin + (size_t)row * DM;
;     f32x4 v[16];
;     float ss = 0.f;
; #pragma unroll
;     for (int i = 0; i < 16; ++i) {
;       v[i] = *reinterpret_cast<const f32x4*>(xr + i * 256 + lane * 4);
;     }
; __device__ __forceinline__ void phase_prep(const Params& p) {
;     ...
; #pragma unroll 1
;   for (;;) {
;     const int tid = opaque_tid();
;     __syncthreads();
;     if (tid == 0) s_pitem = atomicAdd(ctr, 1);
;     __syncthreads();
;     int it = s_pitem;
;     if (it >= N_SP + N_CV + N_RN) break;
;     if (it < N_SP) {
;       ssm_prep_item(p, it);
;     } else if (it < N_SP + N_CV) {
;       it -= N_SP;
;       if (it < CV_IN) cv_in(p, 0, it, tid);
;       else cv_pool(p, 0, it - CV_IN, tid);
;     } else {
;       int row = (it - N_SP - N_CV) * 8 + (tid >> 6);
;       rmsnorm_rows(p.x, p.ln_g, (u16*)(p.ws + WS_H), nullptr, row, row + 1, 1, tid);
;     }
;   }
.LBB0_258:
	s_or_b64 exec, exec, s[6:7]
	s_waitcnt lgkmcnt(0)
	s_barrier
	ds_read_b32 v0, v163 offset:16
	s_movk_i32 s6, 0x603
	s_waitcnt lgkmcnt(0)
	v_cmp_lt_i32_e32 vcc, s6, v0
	v_readfirstlane_b32 s16, v0
	s_mov_b64 s[6:7], -1
	s_cbranch_vccnz .LBB0_253
	s_cmpk_gt_i32 s16, 0x7f
	s_cbranch_scc0 .LBB0_272
	s_cmpk_gt_u32 s16, 0x203
	s_cbranch_scc0 .LBB0_262
	v_ashrrev_i32_e32 v0, 6, v130
	v_lshl_add_u32 v0, s16, 3, v0
	v_add_u32_e32 v132, 0xffffefe0, v0
	v_lshlrev_b32_e32 v0, 2, v130
	v_and_b32_e32 v97, 0xfc, v0
	v_readlane_b32 s64, v254, 33
	v_lshlrev_b32_e32 v162, 2, v97
	v_readlane_b32 s66, v254, 35
	v_readlane_b32 s67, v254, 36
	s_nop 4
	global_load_dwordx4 v[102:105], v162, s[66:67]
	global_load_dwordx4 v[98:101], v162, s[66:67] offset:1024
	global_load_dwordx4 v[88:91], v162, s[66:67] offset:2048
	global_load_dwordx4 v[80:83], v162, s[66:67] offset:3072
	v_lshl_add_u64 v[0:1], s[66:67], 0, v[162:163]
	v_add_co_u32_e32 v2, vcc, 0x1000, v0
	v_readlane_b32 s65, v254, 34
	s_nop 0
	v_addc_co_u32_e32 v3, vcc, 0, v1, vcc
	global_load_dwordx4 v[76:79], v[2:3], off
	global_load_dwordx4 v[68:71], v[2:3], off offset:1024
	global_load_dwordx4 v[56:59], v[2:3], off offset:2048
	global_load_dwordx4 v[40:43], v[2:3], off offset:3072
	v_add_co_u32_e32 v2, vcc, s51, v0
	v_ashrrev_i32_e32 v133, 31, v132
	s_nop 0
	v_addc_co_u32_e32 v3, vcc, 0, v1, vcc
	v_add_co_u32_e32 v0, vcc, s38, v0
	v_lshl_add_u64 v[24:25], s[64:65], 0, v[162:163]
	v_lshlrev_b64 v[26:27], 14, v[132:133]
	v_addc_co_u32_e32 v1, vcc, 0, v1, vcc
	v_lshl_add_u64 v[24:25], v[24:25], 0, v[26:27]
	v_add_co_u32_e32 v26, vcc, s56, v24
	global_load_dwordx4 v[32:35], v[2:3], off offset:1024
	global_load_dwordx4 v[20:23], v[2:3], off offset:2048
	global_load_dwordx4 v[16:19], v[2:3], off offset:3072
	global_load_dwordx4 v[44:47], v[0:1], off offset:-4096
	global_load_dwordx4 v[12:15], v[0:1], off
	global_load_dwordx4 v[8:11], v[0:1], off offset:1024
	global_load_dwordx4 v[4:7], v[0:1], off offset:2048
	s_nop 0
	global_load_dwordx4 v[0:3], v[0:1], off offset:3072
	v_addc_co_u32_e32 v27, vcc, 0, v25, vcc
	v_add_co_u32_e32 v28, vcc, s51, v24
	global_load_dwordx4 v[126:129], v[24:25], off
	global_load_dwordx4 v[122:125], v[24:25], off offset:1024
	global_load_dwordx4 v[118:121], v[24:25], off offset:2048
	global_load_dwordx4 v[114:117], v[24:25], off offset:3072
	v_addc_co_u32_e32 v29, vcc, 0, v25, vcc
	global_load_dwordx4 v[106:109], v[26:27], off offset:1024
	global_load_dwordx4 v[92:95], v[26:27], off offset:2048
	global_load_dwordx4 v[110:113], v[28:29], off offset:-4096
	global_load_dwordx4 v[72:75], v[28:29], off
	global_load_dwordx4 v[64:67], v[28:29], off offset:1024
	global_load_dwordx4 v[60:63], v[28:29], off offset:2048
	global_load_dwordx4 v[52:55], v[28:29], off offset:3072
	v_add_co_u32_e32 v24, vcc, s38, v24
	v_and_b32_e32 v131, 64, v215
	s_nop 0
	v_addc_co_u32_e32 v25, vcc, 0, v25, vcc
	global_load_dwordx4 v[84:87], v[26:27], off offset:3072
	global_load_dwordx4 v[48:51], v[24:25], off
	global_load_dwordx4 v[36:39], v[24:25], off offset:1024
	global_load_dwordx4 v[28:31], v[24:25], off offset:2048
	s_nop 0
	global_load_dwordx4 v[24:27], v[24:25], off offset:3072
	v_add_u32_e32 v131, 64, v131
	v_xor_b32_e32 v134, 32, v215
	v_cmp_lt_i32_e32 vcc, v134, v131
	s_mov_b64 s[54:55], 0x10040100
	s_mov_b64 s[60:61], 0x2e940180
	v_cndmask_b32_e32 v134, v215, v134, vcc
	v_lshlrev_b32_e32 v140, 2, v134
	v_xor_b32_e32 v134, 16, v215
	v_cmp_lt_i32_e32 vcc, v134, v131
	s_mov_b64 s[52:53], 0x10000180
	s_mov_b64 s[46:47], 0x2e900180
	v_cndmask_b32_e32 v134, v215, v134, vcc
	v_lshlrev_b32_e32 v141, 2, v134
	v_xor_b32_e32 v134, 8, v215
	v_cmp_lt_i32_e32 vcc, v134, v131
	s_mov_b64 s[96:97], 0x2e940100
	s_movk_i32 s33, 0x44
	v_cndmask_b32_e32 v134, v215, v134, vcc
	v_lshlrev_b32_e32 v142, 2, v134
	v_xor_b32_e32 v134, 4, v215
	v_cmp_lt_i32_e32 vcc, v134, v131
	s_movk_i32 s0, 0x3c0
	v_lshlrev_b32_e32 v162, 1, v97
	v_cndmask_b32_e32 v134, v215, v134, vcc
	v_lshlrev_b32_e32 v143, 2, v134
	v_xor_b32_e32 v134, 2, v215
	v_cmp_lt_i32_e32 vcc, v134, v131
	v_readlane_b32 s68, v254, 37
	v_readlane_b32 s69, v254, 38
	v_cndmask_b32_e32 v134, v215, v134, vcc
	v_lshlrev_b32_e32 v144, 2, v134
	v_xor_b32_e32 v134, 1, v215
	v_cmp_lt_i32_e32 vcc, v134, v131
	v_readlane_b32 s70, v254, 39
	v_readlane_b32 s71, v254, 40
	v_cndmask_b32_e32 v131, v215, v134, vcc
	v_readlane_b32 s72, v254, 41
	v_readlane_b32 s73, v254, 42
	v_readlane_b32 s74, v254, 43
	v_readlane_b32 s75, v254, 44
	v_readlane_b32 s76, v254, 45
	v_readlane_b32 s77, v254, 46
	v_readlane_b32 s78, v254, 47
	v_readlane_b32 s79, v254, 48
	v_lshlrev_b32_e32 v131, 2, v131
	v_lshl_add_u64 v[134:135], s[14:15], 0, v[162:163]
	s_waitcnt vmcnt(3)
	v_mov_b32_e32 v138, v49
	s_waitcnt vmcnt(2)
; __device__ __forceinline__ void rmsnorm_rows(const float* __restrict__ xin, const float* __restrict__ g, u16* outb, float* outf,
;                                              int row_begin, int row_end, int row_step, const int tidx) {
;     ...
; #pragma unroll
;     for (int i = 0; i < 16; ++i) ss += v[i][0] * v[i][0] + v[i][1] * v[i][1] + v[i][2] * v[i][2] + v[i][3] * v[i][3];
;     ss = wave_sum(ss);
;     float rs = rsqrtf(ss * (1.f / DM) + 1e-6f);
; #pragma unroll
;     for (int i = 0; i < 16; ++i) {
;       f32x4 o = v[i] * rs * ggv[i];
;       if (outb) {
;         u32x2 pk;
;         pk.x = pack2(o[0], o[1]);
;         pk.y = pack2(o[2], o[3]);
;         *reinterpret_cast<u32x2*>(outb + (size_t)row * DM + i * 256 + lane * 4) = pk;
;       } else {
;         *reinterpret_cast<f32x4*>(outf + (size_t)row * DM + i * 256 + lane * 4) = o;
;       }
;     }
	v_mov_b32_e32 v139, v37
	v_mov_b32_e32 v136, v48
	v_mov_b32_e32 v137, v36
	v_pk_mul_f32 v[138:139], v[138:139], v[138:139]
	v_mul_f32_e32 v97, v127, v127
	v_pk_fma_f32 v[136:137], v[136:137], v[136:137], v[138:139]
	v_mov_b32_e32 v138, v50
	v_mov_b32_e32 v139, v38
	v_pk_fma_f32 v[136:137], v[138:139], v[138:139], v[136:137]
	v_mov_b32_e32 v138, v51
	v_mov_b32_e32 v139, v39
	v_pk_fma_f32 v[136:137], v[138:139], v[138:139], v[136:137]
	v_mul_f32_e32 v138, v123, v123
	v_fmac_f32_e32 v97, v126, v126
	v_fmac_f32_e32 v138, v122, v122
	v_fmac_f32_e32 v97, v128, v128
	v_fmac_f32_e32 v138, v124, v124
	v_fmac_f32_e32 v97, v129, v129
	v_fmac_f32_e32 v138, v125, v125
	v_add_f32_e32 v97, v97, v138
	v_mul_f32_e32 v138, v119, v119
	v_fmac_f32_e32 v138, v118, v118
	v_fmac_f32_e32 v138, v120, v120
	v_fmac_f32_e32 v138, v121, v121
	v_add_f32_e32 v97, v97, v138
	v_mul_f32_e32 v138, v115, v115
	v_fmac_f32_e32 v138, v114, v114
	v_fmac_f32_e32 v138, v116, v116
	v_fmac_f32_e32 v138, v117, v117
	v_add_f32_e32 v97, v97, v138
	v_mul_f32_e32 v138, v111, v111
	v_fmac_f32_e32 v138, v110, v110
	v_fmac_f32_e32 v138, v112, v112
	v_fmac_f32_e32 v138, v113, v113
	v_add_f32_e32 v97, v97, v138
	v_mul_f32_e32 v138, v107, v107
	v_fmac_f32_e32 v138, v106, v106
	v_fmac_f32_e32 v138, v108, v108
	v_fmac_f32_e32 v138, v109, v109
	v_add_f32_e32 v97, v97, v138
	v_mul_f32_e32 v138, v93, v93
	v_fmac_f32_e32 v138, v92, v92
	v_fmac_f32_e32 v138, v94, v94
	v_fmac_f32_e32 v138, v95, v95
	v_add_f32_e32 v97, v97, v138
	v_mul_f32_e32 v138, v85, v85
	v_fmac_f32_e32 v138, v84, v84
	v_fmac_f32_e32 v138, v86, v86
	v_fmac_f32_e32 v138, v87, v87
	v_add_f32_e32 v97, v97, v138
	v_mul_f32_e32 v138, v73, v73
	v_fmac_f32_e32 v138, v72, v72
	v_fmac_f32_e32 v138, v74, v74
	v_fmac_f32_e32 v138, v75, v75
	v_add_f32_e32 v97, v97, v138
	v_mul_f32_e32 v138, v65, v65
	v_fmac_f32_e32 v138, v64, v64
	v_fmac_f32_e32 v138, v66, v66
	v_fmac_f32_e32 v138, v67, v67
	v_add_f32_e32 v97, v97, v138
	v_mul_f32_e32 v138, v61, v61
	v_fmac_f32_e32 v138, v60, v60
	v_fmac_f32_e32 v138, v62, v62
	v_fmac_f32_e32 v138, v63, v63
	v_add_f32_e32 v97, v97, v138
	v_mul_f32_e32 v138, v53, v53
	v_fmac_f32_e32 v138, v52, v52
	v_fmac_f32_e32 v138, v54, v54
	v_fmac_f32_e32 v138, v55, v55
	v_add_f32_e32 v97, v97, v138
	v_add_f32_e32 v97, v97, v136
	s_waitcnt vmcnt(1)
	v_mov_b32_e32 v138, v29
	s_waitcnt vmcnt(0)
	v_mov_b32_e32 v139, v25
	v_add_f32_e32 v97, v97, v137
	v_mov_b32_e32 v136, v28
	v_mov_b32_e32 v137, v24
	v_pk_mul_f32 v[138:139], v[138:139], v[138:139]
	s_mov_b64 s[6:7], 0
	v_pk_fma_f32 v[136:137], v[136:137], v[136:137], v[138:139]
	v_mov_b32_e32 v138, v30
	v_mov_b32_e32 v139, v26
	v_pk_fma_f32 v[136:137], v[138:139], v[138:139], v[136:137]
	v_mov_b32_e32 v138, v31
	v_mov_b32_e32 v139, v27
	v_pk_fma_f32 v[136:137], v[138:139], v[138:139], v[136:137]
	s_nop 0
	v_add_f32_e32 v97, v97, v136
	v_add_f32_e32 v97, v97, v137
	ds_bpermute_b32 v136, v140, v97
	s_waitcnt lgkmcnt(0)
	v_add_f32_e32 v97, v97, v136
	ds_bpermute_b32 v136, v141, v97
	s_waitcnt lgkmcnt(0)
	v_add_f32_e32 v97, v97, v136
	ds_bpermute_b32 v136, v142, v97
	s_waitcnt lgkmcnt(0)
	v_add_f32_e32 v97, v97, v136
	ds_bpermute_b32 v136, v143, v97
	s_waitcnt lgkmcnt(0)
	v_add_f32_e32 v97, v97, v136
	ds_bpermute_b32 v136, v144, v97
	s_waitcnt lgkmcnt(0)
	v_add_f32_e32 v97, v97, v136
	ds_bpermute_b32 v131, v131, v97
	s_waitcnt lgkmcnt(0)
	v_add_f32_e32 v97, v97, v131
	v_fmamk_f32 v97, v97, 0x39800000, v211
	v_mul_f32_e32 v131, 0x4b800000, v97
	v_cmp_gt_f32_e32 vcc, s1, v97
	s_nop 1
	v_cndmask_b32_e32 v97, v97, v131, vcc
	v_rsq_f32_e32 v97, v97
	s_nop 0
	v_mul_f32_e32 v131, 0x45800000, v97
	v_cndmask_b32_e32 v136, v97, v131, vcc
	v_pk_mul_f32 v[106:107], v[106:107], v[136:137] op_sel_hi:[1,0]
	v_pk_mul_f32 v[108:109], v[108:109], v[136:137] op_sel_hi:[1,0]
	v_pk_mul_f32 v[68:69], v[68:69], v[106:107]
	v_lshlrev_b64 v[106:107], 13, v[132:133]
	v_pk_mul_f32 v[70:71], v[70:71], v[108:109]
	v_lshl_add_u64 v[106:107], v[134:135], 0, v[106:107]
	v_cvt_pk_bf16_f32 v68, v68, v69
	v_cvt_pk_bf16_f32 v69, v70, v71
	global_store_dwordx2 v[106:107], v[68:69], off offset:2560
	v_pk_mul_f32 v[68:69], v[92:93], v[136:137] op_sel_hi:[1,0]
	v_pk_mul_f32 v[70:71], v[94:95], v[136:137] op_sel_hi:[1,0]
	v_pk_mul_f32 v[56:57], v[56:57], v[68:69]
	v_pk_mul_f32 v[58:59], v[58:59], v[70:71]
	v_cvt_pk_bf16_f32 v56, v56, v57
	v_pk_mul_f32 v[126:127], v[126:127], v[136:137] op_sel_hi:[1,0]
	v_cvt_pk_bf16_f32 v57, v58, v59
	global_store_dwordx2 v[106:107], v[56:57], off offset:3072
	v_pk_mul_f32 v[56:57], v[84:85], v[136:137] op_sel_hi:[1,0]
	v_pk_mul_f32 v[58:59], v[86:87], v[136:137] op_sel_hi:[1,0]
	v_pk_mul_f32 v[40:41], v[40:41], v[56:57]
	v_pk_mul_f32 v[42:43], v[42:43], v[58:59]
	v_cvt_pk_bf16_f32 v40, v40, v41
	v_pk_mul_f32 v[122:123], v[122:123], v[136:137] op_sel_hi:[1,0]
	v_cvt_pk_bf16_f32 v41, v42, v43
	global_store_dwordx2 v[106:107], v[40:41], off offset:3584
	v_pk_mul_f32 v[40:41], v[72:73], v[136:137] op_sel_hi:[1,0]
	v_pk_mul_f32 v[42:43], v[74:75], v[136:137] op_sel_hi:[1,0]
	v_pk_mul_f32 v[40:41], v[44:45], v[40:41]
	v_pk_mul_f32 v[42:43], v[46:47], v[42:43]
	v_cvt_pk_bf16_f32 v40, v40, v41
	v_pk_mul_f32 v[44:45], v[66:67], v[136:137] op_sel_hi:[1,0]
	v_cvt_pk_bf16_f32 v41, v42, v43
	v_add_co_u32_e32 v42, vcc, s56, v106
	v_pk_mul_f32 v[34:35], v[34:35], v[44:45]
	s_nop 0
	v_addc_co_u32_e32 v43, vcc, 0, v107, vcc
	global_store_dwordx2 v[42:43], v[40:41], off
	v_pk_mul_f32 v[40:41], v[64:65], v[136:137] op_sel_hi:[1,0]
	v_pk_mul_f32 v[118:119], v[118:119], v[136:137] op_sel_hi:[1,0]
	v_pk_mul_f32 v[32:33], v[32:33], v[40:41]
	v_pk_mul_f32 v[114:115], v[114:115], v[136:137] op_sel_hi:[1,0]
; __device__ __forceinline__ void rmsnorm_rows(const float* __restrict__ xin, const float* __restrict__ g, u16* outb, float* outf,
;                                              int row_begin, int row_end, int row_step, const int tidx) {
;     ...
;     for (int i = 0; i < 16; ++i) {
;       f32x4 o = v[i] * rs * ggv[i];
;       if (outb) {
;         u32x2 pk;
;         pk.x = pack2(o[0], o[1]);
;         pk.y = pack2(o[2], o[3]);
;         *reinterpret_cast<u32x2*>(outb + (size_t)row * DM + i * 256 + lane * 4) = pk;
;       } else {
;         *reinterpret_cast<f32x4*>(outf + (size_t)row * DM + i * 256 + lane * 4) = o;
;       }
;     }
; __device__ __forceinline__ void cv_in(const Params& p, int layer, int r, const int tid) {
;   int nb = r / (DM / 64), kb = r % (DM / 64);
;   convert_item(p.w_in + (size_t)layer * DM * DIN, DM, DIN, (u16*)(p.ws + WS_WIN + layer * SZ_WIN), kb, nb, 0, tid);
; }
; __device__ __forceinline__ void cv_out(const Params& p, int layer, int r, const int tid) {
;   int nb = r / 64, kb = r % 64;
;   convert_item(p.w_out + (size_t)layer * DM * DM, DM, DM, (u16*)(p.ws + WS_WOUT + layer * SZ_WOUT), kb, nb, 0, tid);
; }
; __device__ __forceinline__ void cv_glu(const Params& p, int layer, int r, const int tid) {
;   int nb = r / 16, kb = r % 16;
;   convert_item(p.w_glu + (size_t)layer * 1024 * 2048, 1024, 2048, (u16*)(p.ws + WS_WGLU + layer * SZ_WGLU), kb, nb, 1, tid);
; }
; __device__ __forceinline__ void cv_pool(const Params& p, int layer, int r, const int tid) {
;   int g = r / 4, kb = r % 4;
;   convert_item(p.w_pool + ((size_t)layer * 4 + g) * 65536, 256, 256, (u16*)(p.ws + WS_WPOOL + layer * SZ_WPOOL) + (size_t)g * 65536, kb,
;                0, 0, tid);
; }
	v_cvt_pk_bf16_f32 v32, v32, v33
	v_cvt_pk_bf16_f32 v33, v34, v35
	global_store_dwordx2 v[42:43], v[32:33], off offset:512
	v_pk_mul_f32 v[32:33], v[60:61], v[136:137] op_sel_hi:[1,0]
	v_pk_mul_f32 v[34:35], v[62:63], v[136:137] op_sel_hi:[1,0]
	v_pk_mul_f32 v[20:21], v[20:21], v[32:33]
	v_pk_mul_f32 v[22:23], v[22:23], v[34:35]
	v_cvt_pk_bf16_f32 v20, v20, v21
	v_pk_mul_f32 v[110:111], v[110:111], v[136:137] op_sel_hi:[1,0]
	v_cvt_pk_bf16_f32 v21, v22, v23
	global_store_dwordx2 v[42:43], v[20:21], off offset:1024
	v_pk_mul_f32 v[20:21], v[52:53], v[136:137] op_sel_hi:[1,0]
	v_pk_mul_f32 v[22:23], v[54:55], v[136:137] op_sel_hi:[1,0]
	v_pk_mul_f32 v[16:17], v[16:17], v[20:21]
	v_pk_mul_f32 v[18:19], v[18:19], v[22:23]
	v_cvt_pk_bf16_f32 v16, v16, v17
	v_pk_mul_f32 v[128:129], v[128:129], v[136:137] op_sel_hi:[1,0]
	v_cvt_pk_bf16_f32 v17, v18, v19
	global_store_dwordx2 v[42:43], v[16:17], off offset:1536
	v_pk_mul_f32 v[16:17], v[48:49], v[136:137] op_sel_hi:[1,0]
	v_pk_mul_f32 v[18:19], v[50:51], v[136:137] op_sel_hi:[1,0]
	v_pk_mul_f32 v[12:13], v[12:13], v[16:17]
	v_pk_mul_f32 v[14:15], v[14:15], v[18:19]
	v_cvt_pk_bf16_f32 v12, v12, v13
	v_pk_mul_f32 v[102:103], v[102:103], v[126:127]
	v_cvt_pk_bf16_f32 v13, v14, v15
	global_store_dwordx2 v[42:43], v[12:13], off offset:2048
	v_pk_mul_f32 v[12:13], v[36:37], v[136:137] op_sel_hi:[1,0]
	v_pk_mul_f32 v[14:15], v[38:39], v[136:137] op_sel_hi:[1,0]
	v_pk_mul_f32 v[8:9], v[8:9], v[12:13]
	v_pk_mul_f32 v[10:11], v[10:11], v[14:15]
	v_cvt_pk_bf16_f32 v8, v8, v9
	v_pk_mul_f32 v[124:125], v[124:125], v[136:137] op_sel_hi:[1,0]
	v_cvt_pk_bf16_f32 v9, v10, v11
	global_store_dwordx2 v[42:43], v[8:9], off offset:2560
	v_pk_mul_f32 v[8:9], v[28:29], v[136:137] op_sel_hi:[1,0]
	v_pk_mul_f32 v[10:11], v[30:31], v[136:137] op_sel_hi:[1,0]
	v_pk_mul_f32 v[4:5], v[4:5], v[8:9]
	v_pk_mul_f32 v[6:7], v[6:7], v[10:11]
	v_cvt_pk_bf16_f32 v4, v4, v5
	v_pk_mul_f32 v[98:99], v[98:99], v[122:123]
	v_cvt_pk_bf16_f32 v5, v6, v7
	global_store_dwordx2 v[42:43], v[4:5], off offset:3072
	v_pk_mul_f32 v[4:5], v[24:25], v[136:137] op_sel_hi:[1,0]
	v_pk_mul_f32 v[120:121], v[120:121], v[136:137] op_sel_hi:[1,0]
	v_pk_mul_f32 v[88:89], v[88:89], v[118:119]
	v_pk_mul_f32 v[116:117], v[116:117], v[136:137] op_sel_hi:[1,0]
	v_pk_mul_f32 v[80:81], v[80:81], v[114:115]
	v_pk_mul_f32 v[112:113], v[112:113], v[136:137] op_sel_hi:[1,0]
	v_pk_mul_f32 v[76:77], v[76:77], v[110:111]
	v_pk_mul_f32 v[6:7], v[26:27], v[136:137] op_sel_hi:[1,0]
	v_pk_mul_f32 v[0:1], v[0:1], v[4:5]
	v_pk_mul_f32 v[104:105], v[104:105], v[128:129]
	v_pk_mul_f32 v[100:101], v[100:101], v[124:125]
	v_pk_mul_f32 v[90:91], v[90:91], v[120:121]
	v_pk_mul_f32 v[82:83], v[82:83], v[116:117]
	v_pk_mul_f32 v[78:79], v[78:79], v[112:113]
	v_cvt_pk_bf16_f32 v102, v102, v103
	v_cvt_pk_bf16_f32 v103, v104, v105
	global_store_dwordx2 v[106:107], v[102:103], off
	v_cvt_pk_bf16_f32 v98, v98, v99
	v_cvt_pk_bf16_f32 v99, v100, v101
	global_store_dwordx2 v[106:107], v[98:99], off offset:512
	v_cvt_pk_bf16_f32 v88, v88, v89
	v_cvt_pk_bf16_f32 v89, v90, v91
	global_store_dwordx2 v[106:107], v[88:89], off offset:1024
	v_cvt_pk_bf16_f32 v80, v80, v81
	v_cvt_pk_bf16_f32 v81, v82, v83
	global_store_dwordx2 v[106:107], v[80:81], off offset:1536
	v_cvt_pk_bf16_f32 v76, v76, v77
	v_cvt_pk_bf16_f32 v77, v78, v79
	global_store_dwordx2 v[106:107], v[76:77], off offset:2048
	v_pk_mul_f32 v[2:3], v[2:3], v[6:7]
	v_cvt_pk_bf16_f32 v0, v0, v1
	s_nop 0
	v_cvt_pk_bf16_f32 v1, v2, v3
	global_store_dwordx2 v[42:43], v[0:1], off offset:3584
.LBB0_262:
	s_andn2_b64 vcc, exec, s[6:7]
	s_cbranch_vccnz .LBB0_271
	s_load_dwordx4 s[76:79], s[88:89], 0x10
	s_load_dwordx2 s[64:65], s[88:89], 0x98
	s_sub_u32 s6, s16, 0x80
	s_mov_b32 s71, 0
	s_waitcnt lgkmcnt(0)
	s_cmp_lt_u32 s6, 0x180
	s_cbranch_scc1 .Lcvp_win0
	s_sub_u32 s6, s6, 0x180
	s_lshl_b32 s72, s6, 18
	s_add_u32 s8, s78, s72
	s_addc_u32 s9, s79, 0
	s_lshl_b32 s72, s6, 17
	s_add_u32 s66, s64, s72
	s_addc_u32 s67, s65, 0
	s_add_u32 s66, s66, 0x10800000
	s_addc_u32 s67, s67, 0
	s_movk_i32 s68, 0x100
	s_movk_i32 s69, 0x100
	s_mov_b32 s72, 0
	s_mov_b32 s73, 0
	s_branch .Lcvp_common
.Lcvp_win0:
	s_mul_i32 s73, s6, 0xab
	s_lshr_b32 s73, s73, 12
	s_mul_i32 s72, s73, 24
	s_sub_u32 s72, s6, s72
	s_mov_b64 s[8:9], s[76:77]
	s_mov_b64 s[66:67], s[64:65]
	s_movk_i32 s68, 0x3000
	s_movk_i32 s69, 0x1000
.Lcvp_common:
	s_lshl_b32 s73, s73, 8
	s_mul_i32 s74, s73, s68
	s_lshl_b32 s75, s72, 9
	s_add_u32 s74, s74, s75
	s_lshl_b32 s74, s74, 2
	s_add_u32 s8, s8, s74
	s_addc_u32 s9, s9, 0
	s_lshl_b32 s10, s68, 2
	v_add_u32_e32 v84, s75, v130
	v_cmp_gt_u32_e32 vcc, s68, v84
	s_and_b64 exec, exec, vcc
	s_cbranch_execz .Lcvp_done
	v_and_b32_e32 v85, 63, v130
	v_sub_u32_e32 v84, v84, v85
	v_lshrrev_b32_e32 v85, 3, v85
	v_add_u32_e32 v84, v84, v85
	s_cmp_eq_u32 s71, 0
	s_cbranch_scc1 .Lcvp_nd
	v_and_b32_e32 v85, 0x3ff, v84
	v_lshrrev_b32_e32 v86, 7, v85
	v_lshlrev_b32_e32 v86, 8, v86
	v_and_b32_e32 v85, 0x7f, v85
	v_lshrrev_b32_e32 v87, 3, v84
	v_and_b32_e32 v87, 0x80, v87
	v_or3_b32 v84, v86, v85, v87
; __device__ __forceinline__ void convert_item(const float* __restrict__ src, int Ksz, int Nsz, u16* __restrict__ dst, int kb, int nb,
;                                              int mode, const int tid) {
;   const int n = nb * NTHR + tid;
;   if (n < Nsz) {
;     const float* sp = src + (size_t)(kb * 64) * Nsz + n;
;     float v[64];
; #pragma unroll
;     for (int j = 0; j < 64; ++j) v[j] = sp[(size_t)j * Nsz];
.Lcvp_nd:
	s_lshl_b32 s74, s69, 1
	s_lshl_b32 s75, s73, 1
	s_add_u32 s66, s66, s75
	s_addc_u32 s67, s67, 0
	s_lshl_b32 s6, s74, 3
	s_mov_b32 s7, 0
	v_mov_b32_e32 v86, s66
	v_mov_b32_e32 v87, s67
	v_mov_b32_e32 v88, s74
	v_mad_u64_u32 v[90:91], vcc, v84, v88, v[86:87]
	v_and_b32_e32 v0, 7, v130
	v_lshlrev_b32_e32 v0, 4, v0
	v_add_co_u32_e32 v84, vcc, v90, v0
	s_nop 1
	v_addc_co_u32_e32 v85, vcc, 0, v91, vcc
	v_lshlrev_b32_e32 v1, 2, v130
	v_lshrrev_b32_e32 v2, 6, v130
	v_mul_u32_u24_e32 v2, 0x2400, v2
	v_and_b32_e32 v3, 63, v130
	v_lshrrev_b32_e32 v89, 3, v3
	v_mul_u32_u24_e32 v89, 0x90, v89
	v_add3_u32 v89, v89, v0, v2
	v_mul_u32_u24_e32 v3, 0x90, v3
	v_add3_u32 v2, v2, v3, 32
	v_add_u32_e32 v3, 32, v89
	global_load_dword v4, v1, s[8:9]
	s_add_u32 s8, s8, s10
	s_addc_u32 s9, s9, 0
	global_load_dword v5, v1, s[8:9]
	s_add_u32 s8, s8, s10
	s_addc_u32 s9, s9, 0
	global_load_dword v6, v1, s[8:9]
	s_add_u32 s8, s8, s10
	s_addc_u32 s9, s9, 0
	global_load_dword v7, v1, s[8:9]
	s_add_u32 s8, s8, s10
	s_addc_u32 s9, s9, 0
	global_load_dword v8, v1, s[8:9]
	s_add_u32 s8, s8, s10
	s_addc_u32 s9, s9, 0
	global_load_dword v9, v1, s[8:9]
	s_add_u32 s8, s8, s10
	s_addc_u32 s9, s9, 0
	global_load_dword v10, v1, s[8:9]
	s_add_u32 s8, s8, s10
	s_addc_u32 s9, s9, 0
	global_load_dword v11, v1, s[8:9]
	s_add_u32 s8, s8, s10
	s_addc_u32 s9, s9, 0
	global_load_dword v12, v1, s[8:9]
	s_add_u32 s8, s8, s10
	s_addc_u32 s9, s9, 0
	global_load_dword v13, v1, s[8:9]
	s_add_u32 s8, s8, s10
	s_addc_u32 s9, s9, 0
	global_load_dword v14, v1, s[8:9]
	s_add_u32 s8, s8, s10
	s_addc_u32 s9, s9, 0
	global_load_dword v15, v1, s[8:9]
	s_add_u32 s8, s8, s10
	s_addc_u32 s9, s9, 0
	global_load_dword v16, v1, s[8:9]
	s_add_u32 s8, s8, s10
	s_addc_u32 s9, s9, 0
	global_load_dword v17, v1, s[8:9]
	s_add_u32 s8, s8, s10
	s_addc_u32 s9, s9, 0
	global_load_dword v18, v1, s[8:9]
	s_add_u32 s8, s8, s10
	s_addc_u32 s9, s9, 0
	global_load_dword v19, v1, s[8:9]
	s_add_u32 s8, s8, s10
	s_addc_u32 s9, s9, 0
	global_load_dword v20, v1, s[8:9]
	s_add_u32 s8, s8, s10
	s_addc_u32 s9, s9, 0
	global_load_dword v21, v1, s[8:9]
	s_add_u32 s8, s8, s10
	s_addc_u32 s9, s9, 0
	global_load_dword v22, v1, s[8:9]
	s_add_u32 s8, s8, s10
	s_addc_u32 s9, s9, 0
	global_load_dword v23, v1, s[8:9]
	s_add_u32 s8, s8, s10
	s_addc_u32 s9, s9, 0
	global_load_dword v24, v1, s[8:9]
	s_add_u32 s8, s8, s10
	s_addc_u32 s9, s9, 0
	global_load_dword v25, v1, s[8:9]
	s_add_u32 s8, s8, s10
	s_addc_u32 s9, s9, 0
	global_load_dword v26, v1, s[8:9]
	s_add_u32 s8, s8, s10
	s_addc_u32 s9, s9, 0
	global_load_dword v27, v1, s[8:9]
	s_add_u32 s8, s8, s10
	s_addc_u32 s9, s9, 0
	global_load_dword v28, v1, s[8:9]
	s_add_u32 s8, s8, s10
	s_addc_u32 s9, s9, 0
	global_load_dword v29, v1, s[8:9]
	s_add_u32 s8, s8, s10
	s_addc_u32 s9, s9, 0
	global_load_dword v30, v1, s[8:9]
	s_add_u32 s8, s8, s10
	s_addc_u32 s9, s9, 0
	global_load_dword v31, v1, s[8:9]
	s_add_u32 s8, s8, s10
	s_addc_u32 s9, s9, 0
	global_load_dword v32, v1, s[8:9]
	s_add_u32 s8, s8, s10
	s_addc_u32 s9, s9, 0
	global_load_dword v33, v1, s[8:9]
	s_add_u32 s8, s8, s10
	s_addc_u32 s9, s9, 0
	global_load_dword v34, v1, s[8:9]
	s_add_u32 s8, s8, s10
	s_addc_u32 s9, s9, 0
	global_load_dword v35, v1, s[8:9]
	s_add_u32 s8, s8, s10
	s_addc_u32 s9, s9, 0
	global_load_dword v36, v1, s[8:9]
	s_add_u32 s8, s8, s10
	s_addc_u32 s9, s9, 0
	global_load_dword v37, v1, s[8:9]
	s_add_u32 s8, s8, s10
	s_addc_u32 s9, s9, 0
	global_load_dword v38, v1, s[8:9]
	s_add_u32 s8, s8, s10
	s_addc_u32 s9, s9, 0
	global_load_dword v39, v1, s[8:9]
	s_add_u32 s8, s8, s10
	s_addc_u32 s9, s9, 0
	global_load_dword v40, v1, s[8:9]
	s_add_u32 s8, s8, s10
	s_addc_u32 s9, s9, 0
	global_load_dword v41, v1, s[8:9]
	s_add_u32 s8, s8, s10
	s_addc_u32 s9, s9, 0
	global_load_dword v42, v1, s[8:9]
	s_add_u32 s8, s8, s10
	s_addc_u32 s9, s9, 0
	global_load_dword v43, v1, s[8:9]
	s_add_u32 s8, s8, s10
	s_addc_u32 s9, s9, 0
	global_load_dword v44, v1, s[8:9]
	s_add_u32 s8, s8, s10
	s_addc_u32 s9, s9, 0
	global_load_dword v45, v1, s[8:9]
	s_add_u32 s8, s8, s10
	s_addc_u32 s9, s9, 0
	global_load_dword v46, v1, s[8:9]
	s_add_u32 s8, s8, s10
	s_addc_u32 s9, s9, 0
	global_load_dword v47, v1, s[8:9]
	s_add_u32 s8, s8, s10
	s_addc_u32 s9, s9, 0
	global_load_dword v48, v1, s[8:9]
	s_add_u32 s8, s8, s10
	s_addc_u32 s9, s9, 0
	global_load_dword v49, v1, s[8:9]
	s_add_u32 s8, s8, s10
	s_addc_u32 s9, s9, 0
	global_load_dword v50, v1, s[8:9]
	s_add_u32 s8, s8, s10
	s_addc_u32 s9, s9, 0
	global_load_dword v51, v1, s[8:9]
	s_add_u32 s8, s8, s10
	s_addc_u32 s9, s9, 0
	global_load_dword v52, v1, s[8:9]
	s_add_u32 s8, s8, s10
	s_addc_u32 s9, s9, 0
	global_load_dword v53, v1, s[8:9]
	s_add_u32 s8, s8, s10
	s_addc_u32 s9, s9, 0
	global_load_dword v54, v1, s[8:9]
	s_add_u32 s8, s8, s10
	s_addc_u32 s9, s9, 0
	global_load_dword v55, v1, s[8:9]
	s_add_u32 s8, s8, s10
	s_addc_u32 s9, s9, 0
	global_load_dword v56, v1, s[8:9]
	s_add_u32 s8, s8, s10
	s_addc_u32 s9, s9, 0
	global_load_dword v57, v1, s[8:9]
	s_add_u32 s8, s8, s10
	s_addc_u32 s9, s9, 0
	global_load_dword v58, v1, s[8:9]
	s_add_u32 s8, s8, s10
	s_addc_u32 s9, s9, 0
	global_load_dword v59, v1, s[8:9]
	s_add_u32 s8, s8, s10
	s_addc_u32 s9, s9, 0
	global_load_dword v60, v1, s[8:9]
	s_add_u32 s8, s8, s10
	s_addc_u32 s9, s9, 0
	global_load_dword v61, v1, s[8:9]
	s_add_u32 s8, s8, s10
	s_addc_u32 s9, s9, 0
	global_load_dword v62, v1, s[8:9]
	s_add_u32 s8, s8, s10
	s_addc_u32 s9, s9, 0
	global_load_dword v63, v1, s[8:9]
	s_add_u32 s8, s8, s10
	s_addc_u32 s9, s9, 0
	global_load_dword v64, v1, s[8:9]
	s_add_u32 s8, s8, s10
	s_addc_u32 s9, s9, 0
	global_load_dword v65, v1, s[8:9]
	s_add_u32 s8, s8, s10
	s_addc_u32 s9, s9, 0
	global_load_dword v66, v1, s[8:9]
	s_add_u32 s8, s8, s10
	s_addc_u32 s9, s9, 0
	global_load_dword v67, v1, s[8:9]
	s_add_u32 s8, s8, s10
	s_addc_u32 s9, s9, 0
	s_waitcnt vmcnt(32)
; __device__ __forceinline__ void convert_item(const float* __restrict__ src, int Ksz, int Nsz, u16* __restrict__ dst, int kb, int nb,
;                                              int mode, const int tid) {
;     ...
; #pragma unroll
;     for (int q = 0; q < 8; ++q) {
;       u32x4 o;
;       o.x = pack2(v[q * 8 + 0], v[q * 8 + 1]);
;       o.y = pack2(v[q * 8 + 2], v[q * 8 + 3]);
;       o.z = pack2(v[q * 8 + 4], v[q * 8 + 5]);
;       o.w = pack2(v[q * 8 + 6], v[q * 8 + 7]);
;       d[q] = o;
;     }
	v_cvt_pk_bf16_f32 v68, v4, v5
	v_cvt_pk_bf16_f32 v69, v6, v7
	v_cvt_pk_bf16_f32 v70, v8, v9
	v_cvt_pk_bf16_f32 v71, v10, v11
	v_cvt_pk_bf16_f32 v72, v12, v13
	v_cvt_pk_bf16_f32 v73, v14, v15
	v_cvt_pk_bf16_f32 v74, v16, v17
	v_cvt_pk_bf16_f32 v75, v18, v19
	v_cvt_pk_bf16_f32 v76, v20, v21
	v_cvt_pk_bf16_f32 v77, v22, v23
	v_cvt_pk_bf16_f32 v78, v24, v25
	v_cvt_pk_bf16_f32 v79, v26, v27
	v_cvt_pk_bf16_f32 v80, v28, v29
	v_cvt_pk_bf16_f32 v81, v30, v31
	v_cvt_pk_bf16_f32 v82, v32, v33
	v_cvt_pk_bf16_f32 v83, v34, v35
	ds_write_b128 v2, v[68:71] offset:0
	ds_write_b128 v2, v[72:75] offset:16
	ds_write_b128 v2, v[76:79] offset:32
	ds_write_b128 v2, v[80:83] offset:48
	global_load_dword v4, v1, s[8:9]
	s_add_u32 s8, s8, s10
	s_addc_u32 s9, s9, 0
	global_load_dword v5, v1, s[8:9]
	s_add_u32 s8, s8, s10
	s_addc_u32 s9, s9, 0
	global_load_dword v6, v1, s[8:9]
	s_add_u32 s8, s8, s10
	s_addc_u32 s9, s9, 0
	global_load_dword v7, v1, s[8:9]
	s_add_u32 s8, s8, s10
	s_addc_u32 s9, s9, 0
	global_load_dword v8, v1, s[8:9]
	s_add_u32 s8, s8, s10
	s_addc_u32 s9, s9, 0
	global_load_dword v9, v1, s[8:9]
	s_add_u32 s8, s8, s10
	s_addc_u32 s9, s9, 0
	global_load_dword v10, v1, s[8:9]
	s_add_u32 s8, s8, s10
	s_addc_u32 s9, s9, 0
	global_load_dword v11, v1, s[8:9]
	s_add_u32 s8, s8, s10
	s_addc_u32 s9, s9, 0
	global_load_dword v12, v1, s[8:9]
	s_add_u32 s8, s8, s10
	s_addc_u32 s9, s9, 0
	global_load_dword v13, v1, s[8:9]
	s_add_u32 s8, s8, s10
	s_addc_u32 s9, s9, 0
	global_load_dword v14, v1, s[8:9]
	s_add_u32 s8, s8, s10
	s_addc_u32 s9, s9, 0
	global_load_dword v15, v1, s[8:9]
	s_add_u32 s8, s8, s10
	s_addc_u32 s9, s9, 0
	global_load_dword v16, v1, s[8:9]
	s_add_u32 s8, s8, s10
	s_addc_u32 s9, s9, 0
	global_load_dword v17, v1, s[8:9]
	s_add_u32 s8, s8, s10
	s_addc_u32 s9, s9, 0
	global_load_dword v18, v1, s[8:9]
	s_add_u32 s8, s8, s10
	s_addc_u32 s9, s9, 0
	global_load_dword v19, v1, s[8:9]
	s_add_u32 s8, s8, s10
	s_addc_u32 s9, s9, 0
	global_load_dword v20, v1, s[8:9]
	s_add_u32 s8, s8, s10
	s_addc_u32 s9, s9, 0
	global_load_dword v21, v1, s[8:9]
	s_add_u32 s8, s8, s10
	s_addc_u32 s9, s9, 0
	global_load_dword v22, v1, s[8:9]
	s_add_u32 s8, s8, s10
	s_addc_u32 s9, s9, 0
	global_load_dword v23, v1, s[8:9]
	s_add_u32 s8, s8, s10
	s_addc_u32 s9, s9, 0
	global_load_dword v24, v1, s[8:9]
	s_add_u32 s8, s8, s10
	s_addc_u32 s9, s9, 0
	global_load_dword v25, v1, s[8:9]
	s_add_u32 s8, s8, s10
	s_addc_u32 s9, s9, 0
	global_load_dword v26, v1, s[8:9]
	s_add_u32 s8, s8, s10
	s_addc_u32 s9, s9, 0
	global_load_dword v27, v1, s[8:9]
	s_add_u32 s8, s8, s10
	s_addc_u32 s9, s9, 0
	global_load_dword v28, v1, s[8:9]
	s_add_u32 s8, s8, s10
	s_addc_u32 s9, s9, 0
	global_load_dword v29, v1, s[8:9]
	s_add_u32 s8, s8, s10
	s_addc_u32 s9, s9, 0
	global_load_dword v30, v1, s[8:9]
	s_add_u32 s8, s8, s10
	s_addc_u32 s9, s9, 0
	global_load_dword v31, v1, s[8:9]
	s_add_u32 s8, s8, s10
	s_addc_u32 s9, s9, 0
	global_load_dword v32, v1, s[8:9]
	s_add_u32 s8, s8, s10
	s_addc_u32 s9, s9, 0
	global_load_dword v33, v1, s[8:9]
	s_add_u32 s8, s8, s10
	s_addc_u32 s9, s9, 0
	global_load_dword v34, v1, s[8:9]
	s_add_u32 s8, s8, s10
	s_addc_u32 s9, s9, 0
	global_load_dword v35, v1, s[8:9]
	s_add_u32 s8, s8, s10
	s_addc_u32 s9, s9, 0
	s_waitcnt vmcnt(32)
	v_cvt_pk_bf16_f32 v100, v36, v37
	v_cvt_pk_bf16_f32 v101, v38, v39
	v_cvt_pk_bf16_f32 v102, v40, v41
	v_cvt_pk_bf16_f32 v103, v42, v43
	v_cvt_pk_bf16_f32 v104, v44, v45
	v_cvt_pk_bf16_f32 v105, v46, v47
	v_cvt_pk_bf16_f32 v106, v48, v49
	v_cvt_pk_bf16_f32 v107, v50, v51
	v_cvt_pk_bf16_f32 v108, v52, v53
	v_cvt_pk_bf16_f32 v109, v54, v55
	v_cvt_pk_bf16_f32 v110, v56, v57
	v_cvt_pk_bf16_f32 v111, v58, v59
	v_cvt_pk_bf16_f32 v112, v60, v61
	v_cvt_pk_bf16_f32 v113, v62, v63
	v_cvt_pk_bf16_f32 v114, v64, v65
	v_cvt_pk_bf16_f32 v115, v66, v67
	ds_write_b128 v2, v[100:103] offset:64
	ds_write_b128 v2, v[104:107] offset:80
	ds_write_b128 v2, v[108:111] offset:96
	ds_write_b128 v2, v[112:115] offset:112
	global_load_dword v36, v1, s[8:9]
	s_add_u32 s8, s8, s10
	s_addc_u32 s9, s9, 0
	global_load_dword v37, v1, s[8:9]
	s_add_u32 s8, s8, s10
	s_addc_u32 s9, s9, 0
	global_load_dword v38, v1, s[8:9]
	s_add_u32 s8, s8, s10
	s_addc_u32 s9, s9, 0
	global_load_dword v39, v1, s[8:9]
	s_add_u32 s8, s8, s10
	s_addc_u32 s9, s9, 0
	global_load_dword v40, v1, s[8:9]
	s_add_u32 s8, s8, s10
	s_addc_u32 s9, s9, 0
	global_load_dword v41, v1, s[8:9]
	s_add_u32 s8, s8, s10
	s_addc_u32 s9, s9, 0
	global_load_dword v42, v1, s[8:9]
	s_add_u32 s8, s8, s10
	s_addc_u32 s9, s9, 0
	global_load_dword v43, v1, s[8:9]
	s_add_u32 s8, s8, s10
	s_addc_u32 s9, s9, 0
	global_load_dword v44, v1, s[8:9]
	s_add_u32 s8, s8, s10
	s_addc_u32 s9, s9, 0
	global_load_dword v45, v1, s[8:9]
	s_add_u32 s8, s8, s10
	s_addc_u32 s9, s9, 0
	global_load_dword v46, v1, s[8:9]
	s_add_u32 s8, s8, s10
	s_addc_u32 s9, s9, 0
	global_load_dword v47, v1, s[8:9]
	s_add_u32 s8, s8, s10
	s_addc_u32 s9, s9, 0
	global_load_dword v48, v1, s[8:9]
	s_add_u32 s8, s8, s10
	s_addc_u32 s9, s9, 0
	global_load_dword v49, v1, s[8:9]
	s_add_u32 s8, s8, s10
	s_addc_u32 s9, s9, 0
	global_load_dword v50, v1, s[8:9]
	s_add_u32 s8, s8, s10
	s_addc_u32 s9, s9, 0
	global_load_dword v51, v1, s[8:9]
	s_add_u32 s8, s8, s10
	s_addc_u32 s9, s9, 0
	global_load_dword v52, v1, s[8:9]
	s_add_u32 s8, s8, s10
	s_addc_u32 s9, s9, 0
	global_load_dword v53, v1, s[8:9]
	s_add_u32 s8, s8, s10
	s_addc_u32 s9, s9, 0
	global_load_dword v54, v1, s[8:9]
	s_add_u32 s8, s8, s10
	s_addc_u32 s9, s9, 0
	global_load_dword v55, v1, s[8:9]
	s_add_u32 s8, s8, s10
	s_addc_u32 s9, s9, 0
	global_load_dword v56, v1, s[8:9]
	s_add_u32 s8, s8, s10
	s_addc_u32 s9, s9, 0
	global_load_dword v57, v1, s[8:9]
	s_add_u32 s8, s8, s10
	s_addc_u32 s9, s9, 0
	global_load_dword v58, v1, s[8:9]
	s_add_u32 s8, s8, s10
	s_addc_u32 s9, s9, 0
	global_load_dword v59, v1, s[8:9]
	s_add_u32 s8, s8, s10
	s_addc_u32 s9, s9, 0
	global_load_dword v60, v1, s[8:9]
	s_add_u32 s8, s8, s10
	s_addc_u32 s9, s9, 0
	global_load_dword v61, v1, s[8:9]
	s_add_u32 s8, s8, s10
	s_addc_u32 s9, s9, 0
	global_load_dword v62, v1, s[8:9]
	s_add_u32 s8, s8, s10
	s_addc_u32 s9, s9, 0
	global_load_dword v63, v1, s[8:9]
	s_add_u32 s8, s8, s10
	s_addc_u32 s9, s9, 0
	global_load_dword v64, v1, s[8:9]
	s_add_u32 s8, s8, s10
	s_addc_u32 s9, s9, 0
	global_load_dword v65, v1, s[8:9]
	s_add_u32 s8, s8, s10
	s_addc_u32 s9, s9, 0
	global_load_dword v66, v1, s[8:9]
	s_add_u32 s8, s8, s10
	s_addc_u32 s9, s9, 0
	global_load_dword v67, v1, s[8:9]
	s_add_u32 s8, s8, s10
	s_addc_u32 s9, s9, 0
	v_mov_b32_e32 v86, v84
	v_mov_b32_e32 v87, v85
	ds_read_b128 v[116:119], v3 offset:0
	ds_read_b128 v[120:123], v3 offset:1152
	ds_read_b128 v[124:127], v3 offset:2304
	ds_read_b128 v[128:131], v3 offset:3456
	s_waitcnt lgkmcnt(0)
; __device__ __forceinline__ void convert_item(const float* __restrict__ src, int Ksz, int Nsz, u16* __restrict__ dst, int kb, int nb,
;                                              int mode, const int tid) {
;     ...
; #pragma unroll
;     for (int q = 0; q < 8; ++q) {
;       u32x4 o;
;       o.x = pack2(v[q * 8 + 0], v[q * 8 + 1]);
;       o.y = pack2(v[q * 8 + 2], v[q * 8 + 3]);
;       o.z = pack2(v[q * 8 + 4], v[q * 8 + 5]);
;       o.w = pack2(v[q * 8 + 6], v[q * 8 + 7]);
;       d[q] = o;
;     }
	global_store_dwordx4 v[86:87], v[116:119], off offset:0
	v_lshl_add_u64 v[86:87], v[86:87], 0, s[6:7]
	global_store_dwordx4 v[86:87], v[120:123], off offset:0
	v_lshl_add_u64 v[86:87], v[86:87], 0, s[6:7]
	global_store_dwordx4 v[86:87], v[124:127], off offset:0
	v_lshl_add_u64 v[86:87], v[86:87], 0, s[6:7]
	global_store_dwordx4 v[86:87], v[128:131], off offset:0
	v_lshl_add_u64 v[86:87], v[86:87], 0, s[6:7]
	ds_read_b128 v[116:119], v3 offset:4608
	ds_read_b128 v[120:123], v3 offset:5760
	ds_read_b128 v[124:127], v3 offset:6912
	ds_read_b128 v[128:131], v3 offset:8064
	s_waitcnt lgkmcnt(0)
	global_store_dwordx4 v[86:87], v[116:119], off offset:0
	v_lshl_add_u64 v[86:87], v[86:87], 0, s[6:7]
	global_store_dwordx4 v[86:87], v[120:123], off offset:0
	v_lshl_add_u64 v[86:87], v[86:87], 0, s[6:7]
	global_store_dwordx4 v[86:87], v[124:127], off offset:0
	v_lshl_add_u64 v[86:87], v[86:87], 0, s[6:7]
	global_store_dwordx4 v[86:87], v[128:131], off offset:0
	v_lshl_add_u64 v[86:87], v[86:87], 0, s[6:7]
	s_waitcnt vmcnt(40)
	v_cvt_pk_bf16_f32 v68, v4, v5
	v_cvt_pk_bf16_f32 v69, v6, v7
	v_cvt_pk_bf16_f32 v70, v8, v9
	v_cvt_pk_bf16_f32 v71, v10, v11
	v_cvt_pk_bf16_f32 v72, v12, v13
	v_cvt_pk_bf16_f32 v73, v14, v15
	v_cvt_pk_bf16_f32 v74, v16, v17
	v_cvt_pk_bf16_f32 v75, v18, v19
	v_cvt_pk_bf16_f32 v76, v20, v21
	v_cvt_pk_bf16_f32 v77, v22, v23
	v_cvt_pk_bf16_f32 v78, v24, v25
	v_cvt_pk_bf16_f32 v79, v26, v27
	v_cvt_pk_bf16_f32 v80, v28, v29
	v_cvt_pk_bf16_f32 v81, v30, v31
	v_cvt_pk_bf16_f32 v82, v32, v33
	v_cvt_pk_bf16_f32 v83, v34, v35
	ds_write_b128 v2, v[68:71] offset:0
	ds_write_b128 v2, v[72:75] offset:16
	ds_write_b128 v2, v[76:79] offset:32
	ds_write_b128 v2, v[80:83] offset:48
	global_load_dword v4, v1, s[8:9]
	s_add_u32 s8, s8, s10
	s_addc_u32 s9, s9, 0
	global_load_dword v5, v1, s[8:9]
	s_add_u32 s8, s8, s10
	s_addc_u32 s9, s9, 0
	global_load_dword v6, v1, s[8:9]
	s_add_u32 s8, s8, s10
	s_addc_u32 s9, s9, 0
	global_load_dword v7, v1, s[8:9]
	s_add_u32 s8, s8, s10
	s_addc_u32 s9, s9, 0
	global_load_dword v8, v1, s[8:9]
	s_add_u32 s8, s8, s10
	s_addc_u32 s9, s9, 0
	global_load_dword v9, v1, s[8:9]
	s_add_u32 s8, s8, s10
	s_addc_u32 s9, s9, 0
	global_load_dword v10, v1, s[8:9]
	s_add_u32 s8, s8, s10
	s_addc_u32 s9, s9, 0
	global_load_dword v11, v1, s[8:9]
	s_add_u32 s8, s8, s10
	s_addc_u32 s9, s9, 0
	global_load_dword v12, v1, s[8:9]
	s_add_u32 s8, s8, s10
	s_addc_u32 s9, s9, 0
	global_load_dword v13, v1, s[8:9]
	s_add_u32 s8, s8, s10
	s_addc_u32 s9, s9, 0
	global_load_dword v14, v1, s[8:9]
	s_add_u32 s8, s8, s10
	s_addc_u32 s9, s9, 0
	global_load_dword v15, v1, s[8:9]
	s_add_u32 s8, s8, s10
	s_addc_u32 s9, s9, 0
	global_load_dword v16, v1, s[8:9]
	s_add_u32 s8, s8, s10
	s_addc_u32 s9, s9, 0
	global_load_dword v17, v1, s[8:9]
	s_add_u32 s8, s8, s10
	s_addc_u32 s9, s9, 0
	global_load_dword v18, v1, s[8:9]
	s_add_u32 s8, s8, s10
	s_addc_u32 s9, s9, 0
	global_load_dword v19, v1, s[8:9]
	s_add_u32 s8, s8, s10
	s_addc_u32 s9, s9, 0
	global_load_dword v20, v1, s[8:9]
	s_add_u32 s8, s8, s10
	s_addc_u32 s9, s9, 0
	global_load_dword v21, v1, s[8:9]
	s_add_u32 s8, s8, s10
	s_addc_u32 s9, s9, 0
	global_load_dword v22, v1, s[8:9]
	s_add_u32 s8, s8, s10
	s_addc_u32 s9, s9, 0
	global_load_dword v23, v1, s[8:9]
	s_add_u32 s8, s8, s10
	s_addc_u32 s9, s9, 0
	global_load_dword v24, v1, s[8:9]
	s_add_u32 s8, s8, s10
	s_addc_u32 s9, s9, 0
	global_load_dword v25, v1, s[8:9]
	s_add_u32 s8, s8, s10
	s_addc_u32 s9, s9, 0
	global_load_dword v26, v1, s[8:9]
	s_add_u32 s8, s8, s10
	s_addc_u32 s9, s9, 0
	global_load_dword v27, v1, s[8:9]
	s_add_u32 s8, s8, s10
	s_addc_u32 s9, s9, 0
	global_load_dword v28, v1, s[8:9]
	s_add_u32 s8, s8, s10
	s_addc_u32 s9, s9, 0
	global_load_dword v29, v1, s[8:9]
	s_add_u32 s8, s8, s10
	s_addc_u32 s9, s9, 0
	global_load_dword v30, v1, s[8:9]
	s_add_u32 s8, s8, s10
	s_addc_u32 s9, s9, 0
	global_load_dword v31, v1, s[8:9]
	s_add_u32 s8, s8, s10
	s_addc_u32 s9, s9, 0
	global_load_dword v32, v1, s[8:9]
	s_add_u32 s8, s8, s10
	s_addc_u32 s9, s9, 0
	global_load_dword v33, v1, s[8:9]
	s_add_u32 s8, s8, s10
	s_addc_u32 s9, s9, 0
	global_load_dword v34, v1, s[8:9]
	s_add_u32 s8, s8, s10
	s_addc_u32 s9, s9, 0
	global_load_dword v35, v1, s[8:9]
	s_add_u32 s8, s8, s10
	s_addc_u32 s9, s9, 0
	s_waitcnt vmcnt(40)
; __device__ __forceinline__ void convert_item(const float* __restrict__ src, int Ksz, int Nsz, u16* __restrict__ dst, int kb, int nb,
;                                              int mode, const int tid) {
;     ...
; #pragma unroll
;     for (int q = 0; q < 8; ++q) {
;       u32x4 o;
;       o.x = pack2(v[q * 8 + 0], v[q * 8 + 1]);
;       o.y = pack2(v[q * 8 + 2], v[q * 8 + 3]);
;       o.z = pack2(v[q * 8 + 4], v[q * 8 + 5]);
;       o.w = pack2(v[q * 8 + 6], v[q * 8 + 7]);
;       d[q] = o;
;     }
	v_cvt_pk_bf16_f32 v100, v36, v37
	v_cvt_pk_bf16_f32 v101, v38, v39
	v_cvt_pk_bf16_f32 v102, v40, v41
	v_cvt_pk_bf16_f32 v103, v42, v43
	v_cvt_pk_bf16_f32 v104, v44, v45
	v_cvt_pk_bf16_f32 v105, v46, v47
	v_cvt_pk_bf16_f32 v106, v48, v49
	v_cvt_pk_bf16_f32 v107, v50, v51
	v_cvt_pk_bf16_f32 v108, v52, v53
	v_cvt_pk_bf16_f32 v109, v54, v55
	v_cvt_pk_bf16_f32 v110, v56, v57
	v_cvt_pk_bf16_f32 v111, v58, v59
	v_cvt_pk_bf16_f32 v112, v60, v61
	v_cvt_pk_bf16_f32 v113, v62, v63
	v_cvt_pk_bf16_f32 v114, v64, v65
	v_cvt_pk_bf16_f32 v115, v66, v67
	ds_write_b128 v2, v[100:103] offset:64
	ds_write_b128 v2, v[104:107] offset:80
	ds_write_b128 v2, v[108:111] offset:96
	ds_write_b128 v2, v[112:115] offset:112
	global_load_dword v36, v1, s[8:9]
	s_add_u32 s8, s8, s10
	s_addc_u32 s9, s9, 0
	global_load_dword v37, v1, s[8:9]
	s_add_u32 s8, s8, s10
	s_addc_u32 s9, s9, 0
	global_load_dword v38, v1, s[8:9]
	s_add_u32 s8, s8, s10
	s_addc_u32 s9, s9, 0
	global_load_dword v39, v1, s[8:9]
	s_add_u32 s8, s8, s10
	s_addc_u32 s9, s9, 0
	global_load_dword v40, v1, s[8:9]
	s_add_u32 s8, s8, s10
	s_addc_u32 s9, s9, 0
	global_load_dword v41, v1, s[8:9]
	s_add_u32 s8, s8, s10
	s_addc_u32 s9, s9, 0
	global_load_dword v42, v1, s[8:9]
	s_add_u32 s8, s8, s10
	s_addc_u32 s9, s9, 0
	global_load_dword v43, v1, s[8:9]
	s_add_u32 s8, s8, s10
	s_addc_u32 s9, s9, 0
	global_load_dword v44, v1, s[8:9]
	s_add_u32 s8, s8, s10
	s_addc_u32 s9, s9, 0
	global_load_dword v45, v1, s[8:9]
	s_add_u32 s8, s8, s10
	s_addc_u32 s9, s9, 0
	global_load_dword v46, v1, s[8:9]
	s_add_u32 s8, s8, s10
	s_addc_u32 s9, s9, 0
	global_load_dword v47, v1, s[8:9]
	s_add_u32 s8, s8, s10
	s_addc_u32 s9, s9, 0
	global_load_dword v48, v1, s[8:9]
	s_add_u32 s8, s8, s10
	s_addc_u32 s9, s9, 0
	global_load_dword v49, v1, s[8:9]
	s_add_u32 s8, s8, s10
	s_addc_u32 s9, s9, 0
	global_load_dword v50, v1, s[8:9]
	s_add_u32 s8, s8, s10
	s_addc_u32 s9, s9, 0
	global_load_dword v51, v1, s[8:9]
	s_add_u32 s8, s8, s10
	s_addc_u32 s9, s9, 0
	global_load_dword v52, v1, s[8:9]
	s_add_u32 s8, s8, s10
	s_addc_u32 s9, s9, 0
	global_load_dword v53, v1, s[8:9]
	s_add_u32 s8, s8, s10
	s_addc_u32 s9, s9, 0
	global_load_dword v54, v1, s[8:9]
	s_add_u32 s8, s8, s10
	s_addc_u32 s9, s9, 0
	global_load_dword v55, v1, s[8:9]
	s_add_u32 s8, s8, s10
	s_addc_u32 s9, s9, 0
	global_load_dword v56, v1, s[8:9]
	s_add_u32 s8, s8, s10
	s_addc_u32 s9, s9, 0
	global_load_dword v57, v1, s[8:9]
	s_add_u32 s8, s8, s10
	s_addc_u32 s9, s9, 0
	global_load_dword v58, v1, s[8:9]
	s_add_u32 s8, s8, s10
	s_addc_u32 s9, s9, 0
	global_load_dword v59, v1, s[8:9]
	s_add_u32 s8, s8, s10
	s_addc_u32 s9, s9, 0
	global_load_dword v60, v1, s[8:9]
	s_add_u32 s8, s8, s10
	s_addc_u32 s9, s9, 0
	global_load_dword v61, v1, s[8:9]
	s_add_u32 s8, s8, s10
	s_addc_u32 s9, s9, 0
	global_load_dword v62, v1, s[8:9]
	s_add_u32 s8, s8, s10
	s_addc_u32 s9, s9, 0
	global_load_dword v63, v1, s[8:9]
	s_add_u32 s8, s8, s10
	s_addc_u32 s9, s9, 0
	global_load_dword v64, v1, s[8:9]
	s_add_u32 s8, s8, s10
	s_addc_u32 s9, s9, 0
	global_load_dword v65, v1, s[8:9]
	s_add_u32 s8, s8, s10
	s_addc_u32 s9, s9, 0
	global_load_dword v66, v1, s[8:9]
	s_add_u32 s8, s8, s10
	s_addc_u32 s9, s9, 0
	global_load_dword v67, v1, s[8:9]
	s_add_u32 s8, s8, s10
	s_addc_u32 s9, s9, 0
	v_mov_b32_e32 v86, v84
	v_mov_b32_e32 v87, v85
	ds_read_b128 v[116:119], v3 offset:0
	ds_read_b128 v[120:123], v3 offset:1152
	ds_read_b128 v[124:127], v3 offset:2304
	ds_read_b128 v[128:131], v3 offset:3456
	s_waitcnt lgkmcnt(0)
	global_store_dwordx4 v[86:87], v[116:119], off offset:128
	v_lshl_add_u64 v[86:87], v[86:87], 0, s[6:7]
	global_store_dwordx4 v[86:87], v[120:123], off offset:128
	v_lshl_add_u64 v[86:87], v[86:87], 0, s[6:7]
	global_store_dwordx4 v[86:87], v[124:127], off offset:128
	v_lshl_add_u64 v[86:87], v[86:87], 0, s[6:7]
	global_store_dwordx4 v[86:87], v[128:131], off offset:128
	v_lshl_add_u64 v[86:87], v[86:87], 0, s[6:7]
	ds_read_b128 v[116:119], v3 offset:4608
	ds_read_b128 v[120:123], v3 offset:5760
	ds_read_b128 v[124:127], v3 offset:6912
	ds_read_b128 v[128:131], v3 offset:8064
	s_waitcnt lgkmcnt(0)
	global_store_dwordx4 v[86:87], v[116:119], off offset:128
	v_lshl_add_u64 v[86:87], v[86:87], 0, s[6:7]
	global_store_dwordx4 v[86:87], v[120:123], off offset:128
	v_lshl_add_u64 v[86:87], v[86:87], 0, s[6:7]
	global_store_dwordx4 v[86:87], v[124:127], off offset:128
	v_lshl_add_u64 v[86:87], v[86:87], 0, s[6:7]
	global_store_dwordx4 v[86:87], v[128:131], off offset:128
	v_lshl_add_u64 v[86:87], v[86:87], 0, s[6:7]
	s_waitcnt vmcnt(40)
; __device__ __forceinline__ void convert_item(const float* __restrict__ src, int Ksz, int Nsz, u16* __restrict__ dst, int kb, int nb,
;                                              int mode, const int tid) {
;     ...
; #pragma unroll
;     for (int q = 0; q < 8; ++q) {
;       u32x4 o;
;       o.x = pack2(v[q * 8 + 0], v[q * 8 + 1]);
;       o.y = pack2(v[q * 8 + 2], v[q * 8 + 3]);
;       o.z = pack2(v[q * 8 + 4], v[q * 8 + 5]);
;       o.w = pack2(v[q * 8 + 6], v[q * 8 + 7]);
;       d[q] = o;
;     }
	v_cvt_pk_bf16_f32 v68, v4, v5
	v_cvt_pk_bf16_f32 v69, v6, v7
	v_cvt_pk_bf16_f32 v70, v8, v9
	v_cvt_pk_bf16_f32 v71, v10, v11
	v_cvt_pk_bf16_f32 v72, v12, v13
	v_cvt_pk_bf16_f32 v73, v14, v15
	v_cvt_pk_bf16_f32 v74, v16, v17
	v_cvt_pk_bf16_f32 v75, v18, v19
	v_cvt_pk_bf16_f32 v76, v20, v21
	v_cvt_pk_bf16_f32 v77, v22, v23
	v_cvt_pk_bf16_f32 v78, v24, v25
	v_cvt_pk_bf16_f32 v79, v26, v27
	v_cvt_pk_bf16_f32 v80, v28, v29
	v_cvt_pk_bf16_f32 v81, v30, v31
	v_cvt_pk_bf16_f32 v82, v32, v33
	v_cvt_pk_bf16_f32 v83, v34, v35
	ds_write_b128 v2, v[68:71] offset:0
	ds_write_b128 v2, v[72:75] offset:16
	ds_write_b128 v2, v[76:79] offset:32
	ds_write_b128 v2, v[80:83] offset:48
	global_load_dword v4, v1, s[8:9]
	s_add_u32 s8, s8, s10
	s_addc_u32 s9, s9, 0
	global_load_dword v5, v1, s[8:9]
	s_add_u32 s8, s8, s10
	s_addc_u32 s9, s9, 0
	global_load_dword v6, v1, s[8:9]
	s_add_u32 s8, s8, s10
	s_addc_u32 s9, s9, 0
	global_load_dword v7, v1, s[8:9]
	s_add_u32 s8, s8, s10
	s_addc_u32 s9, s9, 0
	global_load_dword v8, v1, s[8:9]
	s_add_u32 s8, s8, s10
	s_addc_u32 s9, s9, 0
	global_load_dword v9, v1, s[8:9]
	s_add_u32 s8, s8, s10
	s_addc_u32 s9, s9, 0
	global_load_dword v10, v1, s[8:9]
	s_add_u32 s8, s8, s10
	s_addc_u32 s9, s9, 0
	global_load_dword v11, v1, s[8:9]
	s_add_u32 s8, s8, s10
	s_addc_u32 s9, s9, 0
	global_load_dword v12, v1, s[8:9]
	s_add_u32 s8, s8, s10
	s_addc_u32 s9, s9, 0
	global_load_dword v13, v1, s[8:9]
	s_add_u32 s8, s8, s10
	s_addc_u32 s9, s9, 0
	global_load_dword v14, v1, s[8:9]
	s_add_u32 s8, s8, s10
	s_addc_u32 s9, s9, 0
	global_load_dword v15, v1, s[8:9]
	s_add_u32 s8, s8, s10
	s_addc_u32 s9, s9, 0
	global_load_dword v16, v1, s[8:9]
	s_add_u32 s8, s8, s10
	s_addc_u32 s9, s9, 0
	global_load_dword v17, v1, s[8:9]
	s_add_u32 s8, s8, s10
	s_addc_u32 s9, s9, 0
	global_load_dword v18, v1, s[8:9]
	s_add_u32 s8, s8, s10
	s_addc_u32 s9, s9, 0
	global_load_dword v19, v1, s[8:9]
	s_add_u32 s8, s8, s10
	s_addc_u32 s9, s9, 0
	global_load_dword v20, v1, s[8:9]
	s_add_u32 s8, s8, s10
	s_addc_u32 s9, s9, 0
	global_load_dword v21, v1, s[8:9]
	s_add_u32 s8, s8, s10
	s_addc_u32 s9, s9, 0
	global_load_dword v22, v1, s[8:9]
	s_add_u32 s8, s8, s10
	s_addc_u32 s9, s9, 0
	global_load_dword v23, v1, s[8:9]
	s_add_u32 s8, s8, s10
	s_addc_u32 s9, s9, 0
	global_load_dword v24, v1, s[8:9]
	s_add_u32 s8, s8, s10
	s_addc_u32 s9, s9, 0
	global_load_dword v25, v1, s[8:9]
	s_add_u32 s8, s8, s10
	s_addc_u32 s9, s9, 0
	global_load_dword v26, v1, s[8:9]
	s_add_u32 s8, s8, s10
	s_addc_u32 s9, s9, 0
	global_load_dword v27, v1, s[8:9]
	s_add_u32 s8, s8, s10
	s_addc_u32 s9, s9, 0
	global_load_dword v28, v1, s[8:9]
	s_add_u32 s8, s8, s10
	s_addc_u32 s9, s9, 0
	global_load_dword v29, v1, s[8:9]
	s_add_u32 s8, s8, s10
	s_addc_u32 s9, s9, 0
	global_load_dword v30, v1, s[8:9]
	s_add_u32 s8, s8, s10
	s_addc_u32 s9, s9, 0
	global_load_dword v31, v1, s[8:9]
	s_add_u32 s8, s8, s10
	s_addc_u32 s9, s9, 0
	global_load_dword v32, v1, s[8:9]
	s_add_u32 s8, s8, s10
	s_addc_u32 s9, s9, 0
	global_load_dword v33, v1, s[8:9]
	s_add_u32 s8, s8, s10
	s_addc_u32 s9, s9, 0
	global_load_dword v34, v1, s[8:9]
	s_add_u32 s8, s8, s10
	s_addc_u32 s9, s9, 0
	global_load_dword v35, v1, s[8:9]
	s_add_u32 s8, s8, s10
	s_addc_u32 s9, s9, 0
	s_waitcnt vmcnt(40)
	v_cvt_pk_bf16_f32 v100, v36, v37
	v_cvt_pk_bf16_f32 v101, v38, v39
	v_cvt_pk_bf16_f32 v102, v40, v41
	v_cvt_pk_bf16_f32 v103, v42, v43
	v_cvt_pk_bf16_f32 v104, v44, v45
	v_cvt_pk_bf16_f32 v105, v46, v47
	v_cvt_pk_bf16_f32 v106, v48, v49
	v_cvt_pk_bf16_f32 v107, v50, v51
	v_cvt_pk_bf16_f32 v108, v52, v53
	v_cvt_pk_bf16_f32 v109, v54, v55
	v_cvt_pk_bf16_f32 v110, v56, v57
	v_cvt_pk_bf16_f32 v111, v58, v59
	v_cvt_pk_bf16_f32 v112, v60, v61
	v_cvt_pk_bf16_f32 v113, v62, v63
	v_cvt_pk_bf16_f32 v114, v64, v65
	v_cvt_pk_bf16_f32 v115, v66, v67
	ds_write_b128 v2, v[100:103] offset:64
	ds_write_b128 v2, v[104:107] offset:80
	ds_write_b128 v2, v[108:111] offset:96
	ds_write_b128 v2, v[112:115] offset:112
	global_load_dword v36, v1, s[8:9]
	s_add_u32 s8, s8, s10
	s_addc_u32 s9, s9, 0
	global_load_dword v37, v1, s[8:9]
	s_add_u32 s8, s8, s10
	s_addc_u32 s9, s9, 0
	global_load_dword v38, v1, s[8:9]
	s_add_u32 s8, s8, s10
	s_addc_u32 s9, s9, 0
	global_load_dword v39, v1, s[8:9]
	s_add_u32 s8, s8, s10
	s_addc_u32 s9, s9, 0
	global_load_dword v40, v1, s[8:9]
	s_add_u32 s8, s8, s10
	s_addc_u32 s9, s9, 0
	global_load_dword v41, v1, s[8:9]
	s_add_u32 s8, s8, s10
	s_addc_u32 s9, s9, 0
	global_load_dword v42, v1, s[8:9]
	s_add_u32 s8, s8, s10
	s_addc_u32 s9, s9, 0
	global_load_dword v43, v1, s[8:9]
	s_add_u32 s8, s8, s10
	s_addc_u32 s9, s9, 0
	global_load_dword v44, v1, s[8:9]
	s_add_u32 s8, s8, s10
	s_addc_u32 s9, s9, 0
	global_load_dword v45, v1, s[8:9]
	s_add_u32 s8, s8, s10
	s_addc_u32 s9, s9, 0
	global_load_dword v46, v1, s[8:9]
	s_add_u32 s8, s8, s10
	s_addc_u32 s9, s9, 0
	global_load_dword v47, v1, s[8:9]
	s_add_u32 s8, s8, s10
	s_addc_u32 s9, s9, 0
	global_load_dword v48, v1, s[8:9]
	s_add_u32 s8, s8, s10
	s_addc_u32 s9, s9, 0
	global_load_dword v49, v1, s[8:9]
	s_add_u32 s8, s8, s10
	s_addc_u32 s9, s9, 0
	global_load_dword v50, v1, s[8:9]
	s_add_u32 s8, s8, s10
	s_addc_u32 s9, s9, 0
	global_load_dword v51, v1, s[8:9]
	s_add_u32 s8, s8, s10
	s_addc_u32 s9, s9, 0
	global_load_dword v52, v1, s[8:9]
	s_add_u32 s8, s8, s10
	s_addc_u32 s9, s9, 0
	global_load_dword v53, v1, s[8:9]
	s_add_u32 s8, s8, s10
	s_addc_u32 s9, s9, 0
	global_load_dword v54, v1, s[8:9]
	s_add_u32 s8, s8, s10
	s_addc_u32 s9, s9, 0
	global_load_dword v55, v1, s[8:9]
	s_add_u32 s8, s8, s10
	s_addc_u32 s9, s9, 0
	global_load_dword v56, v1, s[8:9]
	s_add_u32 s8, s8, s10
	s_addc_u32 s9, s9, 0
	global_load_dword v57, v1, s[8:9]
	s_add_u32 s8, s8, s10
	s_addc_u32 s9, s9, 0
	global_load_dword v58, v1, s[8:9]
	s_add_u32 s8, s8, s10
	s_addc_u32 s9, s9, 0
	global_load_dword v59, v1, s[8:9]
	s_add_u32 s8, s8, s10
	s_addc_u32 s9, s9, 0
	global_load_dword v60, v1, s[8:9]
	s_add_u32 s8, s8, s10
	s_addc_u32 s9, s9, 0
	global_load_dword v61, v1, s[8:9]
	s_add_u32 s8, s8, s10
	s_addc_u32 s9, s9, 0
	global_load_dword v62, v1, s[8:9]
	s_add_u32 s8, s8, s10
	s_addc_u32 s9, s9, 0
	global_load_dword v63, v1, s[8:9]
	s_add_u32 s8, s8, s10
	s_addc_u32 s9, s9, 0
	global_load_dword v64, v1, s[8:9]
	s_add_u32 s8, s8, s10
	s_addc_u32 s9, s9, 0
	global_load_dword v65, v1, s[8:9]
	s_add_u32 s8, s8, s10
	s_addc_u32 s9, s9, 0
	global_load_dword v66, v1, s[8:9]
	s_add_u32 s8, s8, s10
	s_addc_u32 s9, s9, 0
	global_load_dword v67, v1, s[8:9]
	s_add_u32 s8, s8, s10
	s_addc_u32 s9, s9, 0
	v_mov_b32_e32 v86, v84
	v_mov_b32_e32 v87, v85
	ds_read_b128 v[116:119], v3 offset:0
	ds_read_b128 v[120:123], v3 offset:1152
	ds_read_b128 v[124:127], v3 offset:2304
	ds_read_b128 v[128:131], v3 offset:3456
	s_waitcnt lgkmcnt(0)
; __device__ __forceinline__ void convert_item(const float* __restrict__ src, int Ksz, int Nsz, u16* __restrict__ dst, int kb, int nb,
;                                              int mode, const int tid) {
;     ...
; #pragma unroll
;     for (int q = 0; q < 8; ++q) {
;       u32x4 o;
;       o.x = pack2(v[q * 8 + 0], v[q * 8 + 1]);
;       o.y = pack2(v[q * 8 + 2], v[q * 8 + 3]);
;       o.z = pack2(v[q * 8 + 4], v[q * 8 + 5]);
;       o.w = pack2(v[q * 8 + 6], v[q * 8 + 7]);
;       d[q] = o;
;     }
; __device__ __forceinline__ void phase_prep(const Params& p) {
;   __shared__ int s_pitem;
;   int* ctr = (int*)(p.ws + WS_CTR) + 8;
;   constexpr int N_SP = 128, N_CV = CV_A, N_RN = T / 8;
; #pragma unroll 1
;   for (;;) {
;     const int tid = opaque_tid();
;     __syncthreads();
;     if (tid == 0) s_pitem = atomicAdd(ctr, 1);
;     __syncthreads();
;     int it = s_pitem;
;     if (it >= N_SP + N_CV + N_RN) break;
	global_store_dwordx4 v[86:87], v[116:119], off offset:256
	v_lshl_add_u64 v[86:87], v[86:87], 0, s[6:7]
	global_store_dwordx4 v[86:87], v[120:123], off offset:256
	v_lshl_add_u64 v[86:87], v[86:87], 0, s[6:7]
	global_store_dwordx4 v[86:87], v[124:127], off offset:256
	v_lshl_add_u64 v[86:87], v[86:87], 0, s[6:7]
	global_store_dwordx4 v[86:87], v[128:131], off offset:256
	v_lshl_add_u64 v[86:87], v[86:87], 0, s[6:7]
	ds_read_b128 v[116:119], v3 offset:4608
	ds_read_b128 v[120:123], v3 offset:5760
	ds_read_b128 v[124:127], v3 offset:6912
	ds_read_b128 v[128:131], v3 offset:8064
	s_waitcnt lgkmcnt(0)
	global_store_dwordx4 v[86:87], v[116:119], off offset:256
	v_lshl_add_u64 v[86:87], v[86:87], 0, s[6:7]
	global_store_dwordx4 v[86:87], v[120:123], off offset:256
	v_lshl_add_u64 v[86:87], v[86:87], 0, s[6:7]
	global_store_dwordx4 v[86:87], v[124:127], off offset:256
	v_lshl_add_u64 v[86:87], v[86:87], 0, s[6:7]
	global_store_dwordx4 v[86:87], v[128:131], off offset:256
	v_lshl_add_u64 v[86:87], v[86:87], 0, s[6:7]
	s_waitcnt vmcnt(40)
	v_cvt_pk_bf16_f32 v68, v4, v5
	v_cvt_pk_bf16_f32 v69, v6, v7
	v_cvt_pk_bf16_f32 v70, v8, v9
	v_cvt_pk_bf16_f32 v71, v10, v11
	v_cvt_pk_bf16_f32 v72, v12, v13
	v_cvt_pk_bf16_f32 v73, v14, v15
	v_cvt_pk_bf16_f32 v74, v16, v17
	v_cvt_pk_bf16_f32 v75, v18, v19
	v_cvt_pk_bf16_f32 v76, v20, v21
	v_cvt_pk_bf16_f32 v77, v22, v23
	v_cvt_pk_bf16_f32 v78, v24, v25
	v_cvt_pk_bf16_f32 v79, v26, v27
	v_cvt_pk_bf16_f32 v80, v28, v29
	v_cvt_pk_bf16_f32 v81, v30, v31
	v_cvt_pk_bf16_f32 v82, v32, v33
	v_cvt_pk_bf16_f32 v83, v34, v35
	ds_write_b128 v2, v[68:71] offset:0
	ds_write_b128 v2, v[72:75] offset:16
	ds_write_b128 v2, v[76:79] offset:32
	ds_write_b128 v2, v[80:83] offset:48
	s_waitcnt vmcnt(8)
	v_cvt_pk_bf16_f32 v100, v36, v37
	v_cvt_pk_bf16_f32 v101, v38, v39
	v_cvt_pk_bf16_f32 v102, v40, v41
	v_cvt_pk_bf16_f32 v103, v42, v43
	v_cvt_pk_bf16_f32 v104, v44, v45
	v_cvt_pk_bf16_f32 v105, v46, v47
	v_cvt_pk_bf16_f32 v106, v48, v49
	v_cvt_pk_bf16_f32 v107, v50, v51
	v_cvt_pk_bf16_f32 v108, v52, v53
	v_cvt_pk_bf16_f32 v109, v54, v55
	v_cvt_pk_bf16_f32 v110, v56, v57
	v_cvt_pk_bf16_f32 v111, v58, v59
	v_cvt_pk_bf16_f32 v112, v60, v61
	v_cvt_pk_bf16_f32 v113, v62, v63
	v_cvt_pk_bf16_f32 v114, v64, v65
	v_cvt_pk_bf16_f32 v115, v66, v67
	ds_write_b128 v2, v[100:103] offset:64
	ds_write_b128 v2, v[104:107] offset:80
	ds_write_b128 v2, v[108:111] offset:96
	ds_write_b128 v2, v[112:115] offset:112
	v_mov_b32_e32 v86, v84
	v_mov_b32_e32 v87, v85
	ds_read_b128 v[116:119], v3 offset:0
	ds_read_b128 v[120:123], v3 offset:1152
	ds_read_b128 v[124:127], v3 offset:2304
	ds_read_b128 v[128:131], v3 offset:3456
	s_waitcnt lgkmcnt(0)
	global_store_dwordx4 v[86:87], v[116:119], off offset:384
	v_lshl_add_u64 v[86:87], v[86:87], 0, s[6:7]
	global_store_dwordx4 v[86:87], v[120:123], off offset:384
	v_lshl_add_u64 v[86:87], v[86:87], 0, s[6:7]
	global_store_dwordx4 v[86:87], v[124:127], off offset:384
	v_lshl_add_u64 v[86:87], v[86:87], 0, s[6:7]
	global_store_dwordx4 v[86:87], v[128:131], off offset:384
	v_lshl_add_u64 v[86:87], v[86:87], 0, s[6:7]
	ds_read_b128 v[116:119], v3 offset:4608
	ds_read_b128 v[120:123], v3 offset:5760
	ds_read_b128 v[124:127], v3 offset:6912
	ds_read_b128 v[128:131], v3 offset:8064
	s_waitcnt lgkmcnt(0)
	global_store_dwordx4 v[86:87], v[116:119], off offset:384
	v_lshl_add_u64 v[86:87], v[86:87], 0, s[6:7]
	global_store_dwordx4 v[86:87], v[120:123], off offset:384
	v_lshl_add_u64 v[86:87], v[86:87], 0, s[6:7]
	global_store_dwordx4 v[86:87], v[124:127], off offset:384
	v_lshl_add_u64 v[86:87], v[86:87], 0, s[6:7]
	global_store_dwordx4 v[86:87], v[128:131], off offset:384
	v_lshl_add_u64 v[86:87], v[86:87], 0, s[6:7]
.Lcvp_done:
	s_mov_b64 exec, -1
	s_mov_b64 s[54:55], 0x10040100
	s_mov_b64 s[60:61], 0x2e940180
	s_mov_b64 s[52:53], 0x10000180
	s_mov_b64 s[46:47], 0x2e900180
	s_movk_i32 s33, 0x44
	s_movk_i32 s0, 0x3c0
	s_mov_b64 s[96:97], 0x2e940100
